# q_up rope epilogue: cos/sin table loads software-pipelined one row-block ahead into free frag VGPRs (16 serialized vmcnt(0) round trips -> counted vmcnt(1))
# speedup vs baseline: 1.0081x; 1.0043x over previous
; __device__ __forceinline__ unsigned cvtpk(float lo, float hi) { f32x2_t v = {lo, hi}; bf16x2_t b = __builtin_convertvector(v, bf16x2_t); return __builtin_bit_cast(unsigned, b); }
;     __device__ __forceinline__ void operator()(const f32x4 (&acc)[2][2][4][2], const Unit& u, int wr, int wc, int fr, int fq) const {
;     ...
;                     const int r = EPI_ROW(u, ai, wr, m, fr);
;                     float v[8];
; #pragma unroll
;                     for (int e = 0; e < 4; ++e) { v[e] = acc[ai][bj][m][0][e]; v[4 + e] = acc[ai][bj][m][1][e]; }
;                     if (isrope) {
;                         const int pos = pos_of(r);
;                         const int i0 = (8 * fq) & 15;
;                         const float* rp = rope + ((size_t)pos * 16 + i0) * 2;
;                         const float sg = (fq < 2) ? -1.f : 1.f;
; #pragma unroll
;                         for (int e2 = 0; e2 < 4; ++e2) {
;                             const f32x4 t4 = *(const f32x4*)(rp + 4 * e2);
;                             const float pv0 = __shfl_xor(v[2 * e2], 32), pv1 = __shfl_xor(v[2 * e2 + 1], 32);
;                             v[2 * e2] = v[2 * e2] * t4[0] + sg * pv0 * t4[1];
;                             v[2 * e2 + 1] = v[2 * e2 + 1] * t4[2] + sg * pv1 * t4[3];
;                         }
;                     }
;                     u32x4 w; w.x = cvtpk(v[0], v[1]); w.y = cvtpk(v[2], v[3]); w.z = cvtpk(v[4], v[5]); w.w = cvtpk(v[6], v[7]);
;                     *(u32x4*)(QC + (size_t)r * 576 + c0) = w;
.LBB0_1016:
	s_lshl_b32 s2, s35, 8
	s_or_b32 s22, s2, s28
	s_cmpk_gt_i32 s22, 0x23f
	v_lshl_add_u32 v171, s8, 8, v4
	s_cbranch_scc1 .LBB0_1035
	s_mul_hi_i32 s2, s22, 0x2aaaaaab
	s_lshr_b32 s3, s2, 31
	s_lshr_b32 s2, s2, 4
	s_add_i32 s2, s2, s3
	s_mulk_i32 s2, 0x60
	s_sub_i32 s8, s22, s2
	s_cmp_eq_u32 s8, 64
	s_cselect_b64 s[2:3], -1, 0
	s_cmp_lg_u32 s8, 64
	s_cbranch_scc1 .LBB0_1019
	v_cmp_gt_i32_e32 vcc, s89, v171
	v_and_b32_e32 v130, 0xfcf, v171
	v_lshlrev_b32_e32 v131, 2, v165
	v_cndmask_b32_e32 v130, v166, v130, vcc
	v_lshl_or_b32 v150, v130, 7, v131
	v_and_b32_e32 v131, 64, v248
	v_xor_b32_e32 v130, 32, v248
	v_add_u32_e32 v131, 64, v131
	v_cmp_lt_i32_e32 vcc, v130, v131
	s_nop 1
	v_cndmask_b32_e32 v130, v248, v130, vcc
	v_lshlrev_b32_e32 v174, 2, v130
	global_load_dwordx4 v[130:133], v150, s[0:1] offset:48
	global_load_dwordx4 v[160:163], v150, s[0:1] offset:32
	global_load_dwordx4 v[156:159], v150, s[0:1] offset:16
	global_load_dwordx4 v[152:155], v150, s[0:1]
	v_or_b32_e32 v192, 16, v171
	v_cmp_gt_i32_e32 vcc, s89, v192
	v_and_b32_e32 v192, 0xfdf, v192
	v_lshlrev_b32_e32 v193, 2, v165
	v_cndmask_b32_e32 v192, v167, v192, vcc
	v_lshl_or_b32 v192, v192, 7, v193
	global_load_dwordx4 v[188:191], v192, s[0:1] offset:48
	global_load_dwordx4 v[184:187], v192, s[0:1] offset:32
	global_load_dwordx4 v[180:183], v192, s[0:1] offset:16
	global_load_dwordx4 v[176:179], v192, s[0:1]
	ds_bpermute_b32 v172, v174, v122
	ds_bpermute_b32 v173, v174, v123
	s_waitcnt lgkmcnt(0)
	v_pk_mul_f32 v[172:173], v[144:145], v[172:173]
	s_waitcnt vmcnt(4)
	v_mov_b32_e32 v151, v154
	v_mov_b32_e32 v154, v153
	v_mov_b32_e32 v150, v152
	v_pk_mul_f32 v[152:153], v[154:155], v[172:173]
	ds_bpermute_b32 v172, v174, v124
	ds_bpermute_b32 v173, v174, v125
	v_mov_b32_e32 v155, v158
	v_mov_b32_e32 v158, v157
	v_mov_b32_e32 v154, v156
	v_pk_fma_f32 v[122:123], v[122:123], v[150:151], v[152:153]
	s_waitcnt lgkmcnt(0)
	v_pk_mul_f32 v[172:173], v[144:145], v[172:173]
	s_nop 0
	v_pk_mul_f32 v[156:157], v[158:159], v[172:173]
	ds_bpermute_b32 v172, v174, v126
	ds_bpermute_b32 v173, v174, v127
	v_mov_b32_e32 v159, v162
	v_mov_b32_e32 v162, v161
	v_mov_b32_e32 v158, v160
	v_pk_fma_f32 v[124:125], v[124:125], v[154:155], v[156:157]
	s_waitcnt lgkmcnt(0)
	v_pk_mul_f32 v[172:173], v[144:145], v[172:173]
	s_nop 0
	v_pk_mul_f32 v[160:161], v[162:163], v[172:173]
	ds_bpermute_b32 v162, v174, v128
	ds_bpermute_b32 v163, v174, v129
	v_mul_f32_e32 v128, v128, v130
	v_pk_fma_f32 v[126:127], v[126:127], v[158:159], v[160:161]
	s_waitcnt lgkmcnt(1)
	v_mul_f32_e32 v130, v144, v162
	s_waitcnt lgkmcnt(0)
	v_mul_f32_e32 v163, v144, v163
	v_mov_b32_e32 v162, v129
	v_pk_mul_f32 v[132:133], v[132:133], v[162:163]
	v_mul_f32_e32 v130, v131, v130
	v_mov_b32_e32 v129, v132
	v_mov_b32_e32 v131, v133
	v_pk_add_f32 v[128:129], v[128:129], v[130:131]
.LBB0_1019:
	v_or_b32_e32 v130, s22, v142
	v_cvt_pk_bf16_f32 v122, v122, v123
	v_cvt_pk_bf16_f32 v123, v124, v125
	v_cvt_pk_bf16_f32 v124, v126, v127
	v_mov_b64_e32 v[126:127], s[58:59]
	v_ashrrev_i32_e32 v131, 31, v130
	v_mad_i64_i32 v[126:127], s[36:37], v171, s57, v[126:127]
	v_cvt_pk_bf16_f32 v125, v128, v129
	v_lshl_add_u64 v[126:127], v[130:131], 1, v[126:127]
	global_store_dwordx4 v[126:127], v[122:125], off
	s_nop 1
	v_cndmask_b32_e64 v122, 0, 1, s[2:3]
	v_cmp_ne_u32_e64 s[40:41], 1, v122
	s_andn2_b64 vcc, exec, s[2:3]
	v_or_b32_e32 v158, 16, v171
	s_cbranch_vccnz .LBB0_1021
	v_cmp_gt_i32_e32 vcc, s89, v158
	v_and_b32_e32 v122, 0xfdf, v158
	v_lshlrev_b32_e32 v123, 2, v165
	v_cndmask_b32_e32 v122, v167, v122, vcc
	v_lshl_or_b32 v126, v122, 7, v123
	v_and_b32_e32 v123, 64, v248
	v_xor_b32_e32 v122, 32, v248
	v_add_u32_e32 v123, 64, v123
	v_cmp_lt_i32_e32 vcc, v122, v123
	s_nop 1
	v_cndmask_b32_e32 v122, v248, v122, vcc
	v_lshlrev_b32_e32 v159, 2, v122
	ds_bpermute_b32 v128, v159, v118
	ds_bpermute_b32 v129, v159, v119
	s_waitcnt lgkmcnt(0)
	v_pk_mul_f32 v[128:129], v[144:145], v[128:129]
	s_waitcnt vmcnt(1)
	v_mov_b64_e32 v[122:123], v[188:189]
	v_mov_b64_e32 v[124:125], v[190:191]
	v_mov_b64_e32 v[154:155], v[184:185]
	v_mov_b64_e32 v[156:157], v[186:187]
	v_mov_b64_e32 v[150:151], v[180:181]
	v_mov_b64_e32 v[152:153], v[182:183]
	v_mov_b64_e32 v[160:161], v[176:177]
	v_mov_b64_e32 v[162:163], v[178:179]
	v_or_b32_e32 v192, 32, v171
	v_cmp_gt_i32_e32 vcc, s89, v192
	v_and_b32_e32 v192, 0xfef, v192
	v_lshlrev_b32_e32 v193, 2, v165
	v_cndmask_b32_e32 v192, v168, v192, vcc
	v_lshl_or_b32 v192, v192, 7, v193
	global_load_dwordx4 v[188:191], v192, s[0:1] offset:48
	global_load_dwordx4 v[184:187], v192, s[0:1] offset:32
	global_load_dwordx4 v[180:183], v192, s[0:1] offset:16
	global_load_dwordx4 v[176:179], v192, s[0:1]
	v_mov_b32_e32 v133, v152
	v_mov_b32_e32 v126, v160
	v_mov_b32_e32 v127, v162
	v_mov_b32_e32 v162, v161
	ds_bpermute_b32 v160, v159, v120
	ds_bpermute_b32 v161, v159, v121
	v_mov_b32_e32 v152, v151
	v_mov_b32_e32 v132, v150
	v_pk_mul_f32 v[128:129], v[162:163], v[128:129]
	s_waitcnt lgkmcnt(0)
	v_pk_mul_f32 v[160:161], v[144:145], v[160:161]
	s_nop 0
	v_pk_mul_f32 v[150:151], v[152:153], v[160:161]
	ds_bpermute_b32 v160, v159, v114
	ds_bpermute_b32 v161, v159, v115
	v_mov_b32_e32 v153, v156
	v_mov_b32_e32 v156, v155
	v_mov_b32_e32 v152, v154
	v_pk_fma_f32 v[118:119], v[118:119], v[126:127], v[128:129]
	s_waitcnt lgkmcnt(0)
	v_pk_mul_f32 v[160:161], v[144:145], v[160:161]
	v_pk_fma_f32 v[120:121], v[120:121], v[132:133], v[150:151]
	v_pk_mul_f32 v[154:155], v[156:157], v[160:161]
	ds_bpermute_b32 v156, v159, v116
	ds_bpermute_b32 v157, v159, v117
	v_mul_f32_e32 v116, v116, v122
	v_pk_fma_f32 v[114:115], v[114:115], v[152:153], v[154:155]
	s_waitcnt lgkmcnt(1)
	v_mul_f32_e32 v122, v144, v156
	s_waitcnt lgkmcnt(0)
	v_mul_f32_e32 v157, v144, v157
	v_mov_b32_e32 v156, v117
	v_pk_mul_f32 v[124:125], v[124:125], v[156:157]
	v_mul_f32_e32 v122, v123, v122
	v_mov_b32_e32 v117, v124
	v_mov_b32_e32 v123, v125
	v_pk_add_f32 v[116:117], v[116:117], v[122:123]
; __device__ __forceinline__ unsigned cvtpk(float lo, float hi) { f32x2_t v = {lo, hi}; bf16x2_t b = __builtin_convertvector(v, bf16x2_t); return __builtin_bit_cast(unsigned, b); }
;     __device__ __forceinline__ void operator()(const f32x4 (&acc)[2][2][4][2], const Unit& u, int wr, int wc, int fr, int fq) const {
;     ...
;                     const int r = EPI_ROW(u, ai, wr, m, fr);
;                     float v[8];
; #pragma unroll
;                     for (int e = 0; e < 4; ++e) { v[e] = acc[ai][bj][m][0][e]; v[4 + e] = acc[ai][bj][m][1][e]; }
;                     if (isrope) {
;                         const int pos = pos_of(r);
;                         const int i0 = (8 * fq) & 15;
;                         const float* rp = rope + ((size_t)pos * 16 + i0) * 2;
;                         const float sg = (fq < 2) ? -1.f : 1.f;
; #pragma unroll
;                         for (int e2 = 0; e2 < 4; ++e2) {
;                             const f32x4 t4 = *(const f32x4*)(rp + 4 * e2);
;                             const float pv0 = __shfl_xor(v[2 * e2], 32), pv1 = __shfl_xor(v[2 * e2 + 1], 32);
;                             v[2 * e2] = v[2 * e2] * t4[0] + sg * pv0 * t4[1];
;                             v[2 * e2 + 1] = v[2 * e2 + 1] * t4[2] + sg * pv1 * t4[3];
;                         }
;                     }
;                     u32x4 w; w.x = cvtpk(v[0], v[1]); w.y = cvtpk(v[2], v[3]); w.z = cvtpk(v[4], v[5]); w.w = cvtpk(v[6], v[7]);
;                     *(u32x4*)(QC + (size_t)r * 576 + c0) = w;
.LBB0_1021:
	v_cvt_pk_bf16_f32 v118, v118, v119
	v_cvt_pk_bf16_f32 v119, v120, v121
	v_cvt_pk_bf16_f32 v120, v114, v115
	v_mov_b64_e32 v[114:115], s[58:59]
	v_mad_i64_i32 v[114:115], s[2:3], v158, s57, v[114:115]
	v_cvt_pk_bf16_f32 v121, v116, v117
	v_lshl_add_u64 v[114:115], v[130:131], 1, v[114:115]
	global_store_dwordx4 v[114:115], v[118:121], off
	s_and_b64 vcc, exec, s[40:41]
	v_or_b32_e32 v150, 32, v171
	s_cbranch_vccnz .LBB0_1023
	v_cmp_gt_i32_e32 vcc, s89, v150
	v_and_b32_e32 v114, 0xfef, v150
	v_lshlrev_b32_e32 v115, 2, v165
	v_cndmask_b32_e32 v114, v168, v114, vcc
	v_lshl_or_b32 v118, v114, 7, v115
	v_and_b32_e32 v115, 64, v248
	v_xor_b32_e32 v114, 32, v248
	v_add_u32_e32 v115, 64, v115
	v_cmp_lt_i32_e32 vcc, v114, v115
	s_nop 1
	v_cndmask_b32_e32 v114, v248, v114, vcc
	v_lshlrev_b32_e32 v132, 2, v114
	ds_bpermute_b32 v128, v132, v110
	ds_bpermute_b32 v129, v132, v111
	ds_bpermute_b32 v133, v132, v108
	s_waitcnt lgkmcnt(0)
	v_pk_mul_f32 v[128:129], v[144:145], v[128:129]
	s_waitcnt vmcnt(1)
	v_mov_b64_e32 v[114:115], v[188:189]
	v_mov_b64_e32 v[116:117], v[190:191]
	v_mov_b64_e32 v[152:153], v[184:185]
	v_mov_b64_e32 v[154:155], v[186:187]
	v_mov_b64_e32 v[124:125], v[180:181]
	v_mov_b64_e32 v[126:127], v[182:183]
	v_mov_b64_e32 v[120:121], v[176:177]
	v_mov_b64_e32 v[122:123], v[178:179]
	v_or_b32_e32 v192, 48, v171
	v_cmp_gt_i32_e32 vcc, s89, v192
	v_and_b32_e32 v192, 0xfff, v192
	v_lshlrev_b32_e32 v193, 2, v165
	v_cndmask_b32_e32 v192, v169, v192, vcc
	v_lshl_or_b32 v192, v192, 7, v193
	global_load_dwordx4 v[188:191], v192, s[0:1] offset:48
	global_load_dwordx4 v[184:187], v192, s[0:1] offset:32
	global_load_dwordx4 v[180:183], v192, s[0:1] offset:16
	global_load_dwordx4 v[176:179], v192, s[0:1]
	v_mul_f32_e32 v108, v108, v114
	v_mul_f32_e32 v114, v144, v133
	v_mul_f32_e32 v114, v115, v114
	v_mov_b32_e32 v119, v122
	v_mov_b32_e32 v122, v121
	v_mov_b32_e32 v118, v120
	v_pk_mul_f32 v[120:121], v[122:123], v[128:129]
	ds_bpermute_b32 v128, v132, v112
	ds_bpermute_b32 v129, v132, v113
	v_mov_b32_e32 v123, v126
	v_mov_b32_e32 v126, v125
	v_mov_b32_e32 v122, v124
	v_pk_fma_f32 v[110:111], v[110:111], v[118:119], v[120:121]
	s_waitcnt lgkmcnt(0)
	v_pk_mul_f32 v[128:129], v[144:145], v[128:129]
	s_nop 0
	v_pk_mul_f32 v[124:125], v[126:127], v[128:129]
	ds_bpermute_b32 v128, v132, v106
	ds_bpermute_b32 v129, v132, v107
	ds_bpermute_b32 v132, v132, v109
	v_mov_b32_e32 v127, v154
	v_mov_b32_e32 v154, v153
	v_mov_b32_e32 v126, v152
	s_waitcnt lgkmcnt(1)
	v_pk_mul_f32 v[128:129], v[144:145], v[128:129]
	s_waitcnt lgkmcnt(0)
	v_mul_f32_e32 v133, v144, v132
	v_mov_b32_e32 v132, v109
	v_pk_mul_f32 v[116:117], v[116:117], v[132:133]
	v_pk_mul_f32 v[128:129], v[154:155], v[128:129]
	v_mov_b32_e32 v109, v116
	v_mov_b32_e32 v115, v117
	v_pk_fma_f32 v[112:113], v[112:113], v[122:123], v[124:125]
	v_pk_fma_f32 v[106:107], v[106:107], v[126:127], v[128:129]
	v_pk_add_f32 v[108:109], v[108:109], v[114:115]
.LBB0_1023:
	v_cvt_pk_bf16_f32 v110, v110, v111
	v_cvt_pk_bf16_f32 v111, v112, v113
	v_cvt_pk_bf16_f32 v112, v106, v107
	v_mov_b64_e32 v[106:107], s[58:59]
	v_mad_i64_i32 v[106:107], s[2:3], v150, s57, v[106:107]
	v_cvt_pk_bf16_f32 v113, v108, v109
	v_lshl_add_u64 v[106:107], v[130:131], 1, v[106:107]
	global_store_dwordx4 v[106:107], v[110:113], off
	s_and_b64 vcc, exec, s[40:41]
	v_or_b32_e32 v124, 48, v171
	s_cbranch_vccnz .LBB0_1025
	v_cmp_gt_i32_e32 vcc, s89, v124
	v_and_b32_e32 v106, 0xfff, v124
	v_lshlrev_b32_e32 v107, 2, v165
	v_cndmask_b32_e32 v106, v169, v106, vcc
	v_lshl_or_b32 v110, v106, 7, v107
	v_and_b32_e32 v107, 64, v248
	v_xor_b32_e32 v106, 32, v248
	v_add_u32_e32 v107, 64, v107
	v_cmp_lt_i32_e32 vcc, v106, v107
	s_nop 1
	v_cndmask_b32_e32 v106, v248, v106, vcc
	v_lshlrev_b32_e32 v125, 2, v106
	ds_bpermute_b32 v126, v125, v102
	ds_bpermute_b32 v127, v125, v103
	s_waitcnt lgkmcnt(0)
	v_pk_mul_f32 v[126:127], v[144:145], v[126:127]
	s_waitcnt vmcnt(1)
	v_mov_b64_e32 v[106:107], v[188:189]
	v_mov_b64_e32 v[108:109], v[190:191]
	v_mov_b64_e32 v[120:121], v[184:185]
	v_mov_b64_e32 v[122:123], v[186:187]
	v_mov_b64_e32 v[116:117], v[180:181]
	v_mov_b64_e32 v[118:119], v[182:183]
	v_mov_b64_e32 v[112:113], v[176:177]
	v_mov_b64_e32 v[114:115], v[178:179]
	v_add_u32_e32 v192, 0x80, v171
	v_cmp_gt_i32_e32 vcc, s89, v192
	v_and_b32_e32 v192, 0xfcf, v192
	v_lshlrev_b32_e32 v193, 2, v165
	v_cndmask_b32_e32 v192, v166, v192, vcc
	v_lshl_or_b32 v192, v192, 7, v193
	global_load_dwordx4 v[188:191], v192, s[0:1] offset:48
	global_load_dwordx4 v[184:187], v192, s[0:1] offset:32
	global_load_dwordx4 v[180:183], v192, s[0:1] offset:16
	global_load_dwordx4 v[176:179], v192, s[0:1]
	v_mov_b32_e32 v111, v114
	v_mov_b32_e32 v114, v113
	v_mov_b32_e32 v110, v112
	v_pk_mul_f32 v[112:113], v[114:115], v[126:127]
	ds_bpermute_b32 v126, v125, v104
	ds_bpermute_b32 v127, v125, v105
	v_mov_b32_e32 v115, v118
	v_mov_b32_e32 v118, v117
	v_mov_b32_e32 v114, v116
	v_pk_fma_f32 v[102:103], v[102:103], v[110:111], v[112:113]
	s_waitcnt lgkmcnt(0)
	v_pk_mul_f32 v[126:127], v[144:145], v[126:127]
	s_nop 0
	v_pk_mul_f32 v[116:117], v[118:119], v[126:127]
	ds_bpermute_b32 v126, v125, v98
	ds_bpermute_b32 v127, v125, v99
	v_mov_b32_e32 v119, v122
	v_mov_b32_e32 v122, v121
	v_mov_b32_e32 v118, v120
	v_pk_fma_f32 v[104:105], v[104:105], v[114:115], v[116:117]
	s_waitcnt lgkmcnt(0)
	v_pk_mul_f32 v[126:127], v[144:145], v[126:127]
	s_nop 0
	v_pk_mul_f32 v[120:121], v[122:123], v[126:127]
	ds_bpermute_b32 v122, v125, v100
	ds_bpermute_b32 v123, v125, v101
	v_mul_f32_e32 v100, v100, v106
	v_pk_fma_f32 v[98:99], v[98:99], v[118:119], v[120:121]
	s_waitcnt lgkmcnt(1)
	v_mul_f32_e32 v106, v144, v122
	s_waitcnt lgkmcnt(0)
	v_mul_f32_e32 v123, v144, v123
	v_mov_b32_e32 v122, v101
	v_pk_mul_f32 v[108:109], v[108:109], v[122:123]
	v_mul_f32_e32 v106, v107, v106
	v_mov_b32_e32 v101, v108
	v_mov_b32_e32 v107, v109
	v_pk_add_f32 v[100:101], v[100:101], v[106:107]
; __device__ __forceinline__ unsigned cvtpk(float lo, float hi) { f32x2_t v = {lo, hi}; bf16x2_t b = __builtin_convertvector(v, bf16x2_t); return __builtin_bit_cast(unsigned, b); }
;     __device__ __forceinline__ void operator()(const f32x4 (&acc)[2][2][4][2], const Unit& u, int wr, int wc, int fr, int fq) const {
;     ...
;                     const int r = EPI_ROW(u, ai, wr, m, fr);
;                     float v[8];
; #pragma unroll
;                     for (int e = 0; e < 4; ++e) { v[e] = acc[ai][bj][m][0][e]; v[4 + e] = acc[ai][bj][m][1][e]; }
;                     if (isrope) {
;                         const int pos = pos_of(r);
;                         const int i0 = (8 * fq) & 15;
;                         const float* rp = rope + ((size_t)pos * 16 + i0) * 2;
;                         const float sg = (fq < 2) ? -1.f : 1.f;
; #pragma unroll
;                         for (int e2 = 0; e2 < 4; ++e2) {
;                             const f32x4 t4 = *(const f32x4*)(rp + 4 * e2);
;                             const float pv0 = __shfl_xor(v[2 * e2], 32), pv1 = __shfl_xor(v[2 * e2 + 1], 32);
;                             v[2 * e2] = v[2 * e2] * t4[0] + sg * pv0 * t4[1];
;                             v[2 * e2 + 1] = v[2 * e2 + 1] * t4[2] + sg * pv1 * t4[3];
;                         }
;                     }
;                     u32x4 w; w.x = cvtpk(v[0], v[1]); w.y = cvtpk(v[2], v[3]); w.z = cvtpk(v[4], v[5]); w.w = cvtpk(v[6], v[7]);
;                     *(u32x4*)(QC + (size_t)r * 576 + c0) = w;
.LBB0_1025:
	v_cvt_pk_bf16_f32 v102, v102, v103
	v_cvt_pk_bf16_f32 v103, v104, v105
	v_cvt_pk_bf16_f32 v104, v98, v99
	v_mov_b64_e32 v[98:99], s[58:59]
	v_mad_i64_i32 v[98:99], s[2:3], v124, s57, v[98:99]
	v_cvt_pk_bf16_f32 v105, v100, v101
	v_lshl_add_u64 v[98:99], v[130:131], 1, v[98:99]
	global_store_dwordx4 v[98:99], v[102:105], off
	s_and_b64 vcc, exec, s[40:41]
	v_add_u32_e32 v116, 0x80, v171
	s_cbranch_vccnz .LBB0_1027
	v_cmp_gt_i32_e32 vcc, s89, v116
	v_and_b32_e32 v98, 0xfcf, v116
	v_lshlrev_b32_e32 v99, 2, v165
	v_cndmask_b32_e32 v98, v166, v98, vcc
	v_lshl_or_b32 v102, v98, 7, v99
	v_and_b32_e32 v99, 64, v248
	v_xor_b32_e32 v98, 32, v248
	v_add_u32_e32 v99, 64, v99
	v_cmp_lt_i32_e32 vcc, v98, v99
	s_nop 1
	v_cndmask_b32_e32 v98, v248, v98, vcc
	v_lshlrev_b32_e32 v117, 2, v98
	ds_bpermute_b32 v118, v117, v94
	ds_bpermute_b32 v119, v117, v95
	s_waitcnt lgkmcnt(0)
	v_pk_mul_f32 v[118:119], v[144:145], v[118:119]
	s_waitcnt vmcnt(1)
	v_mov_b64_e32 v[98:99], v[188:189]
	v_mov_b64_e32 v[100:101], v[190:191]
	v_mov_b64_e32 v[112:113], v[184:185]
	v_mov_b64_e32 v[114:115], v[186:187]
	v_mov_b64_e32 v[108:109], v[180:181]
	v_mov_b64_e32 v[110:111], v[182:183]
	v_mov_b64_e32 v[104:105], v[176:177]
	v_mov_b64_e32 v[106:107], v[178:179]
	v_add_u32_e32 v192, 0x90, v171
	v_cmp_gt_i32_e32 vcc, s89, v192
	v_and_b32_e32 v192, 0xfdf, v192
	v_lshlrev_b32_e32 v193, 2, v165
	v_cndmask_b32_e32 v192, v167, v192, vcc
	v_lshl_or_b32 v192, v192, 7, v193
	global_load_dwordx4 v[188:191], v192, s[0:1] offset:48
	global_load_dwordx4 v[184:187], v192, s[0:1] offset:32
	global_load_dwordx4 v[180:183], v192, s[0:1] offset:16
	global_load_dwordx4 v[176:179], v192, s[0:1]
	v_mov_b32_e32 v103, v106
	v_mov_b32_e32 v106, v105
	v_mov_b32_e32 v102, v104
	v_pk_mul_f32 v[104:105], v[106:107], v[118:119]
	ds_bpermute_b32 v118, v117, v96
	ds_bpermute_b32 v119, v117, v97
	v_mov_b32_e32 v107, v110
	v_mov_b32_e32 v110, v109
	v_mov_b32_e32 v106, v108
	v_pk_fma_f32 v[94:95], v[94:95], v[102:103], v[104:105]
	s_waitcnt lgkmcnt(0)
	v_pk_mul_f32 v[118:119], v[144:145], v[118:119]
	s_nop 0
	v_pk_mul_f32 v[108:109], v[110:111], v[118:119]
	ds_bpermute_b32 v118, v117, v90
	ds_bpermute_b32 v119, v117, v91
	v_mov_b32_e32 v111, v114
	v_mov_b32_e32 v114, v113
	v_mov_b32_e32 v110, v112
	v_pk_fma_f32 v[96:97], v[96:97], v[106:107], v[108:109]
	s_waitcnt lgkmcnt(0)
	v_pk_mul_f32 v[118:119], v[144:145], v[118:119]
	s_nop 0
	v_pk_mul_f32 v[112:113], v[114:115], v[118:119]
	ds_bpermute_b32 v114, v117, v92
	ds_bpermute_b32 v115, v117, v93
	v_mul_f32_e32 v92, v92, v98
	v_pk_fma_f32 v[90:91], v[90:91], v[110:111], v[112:113]
	s_waitcnt lgkmcnt(1)
	v_mul_f32_e32 v98, v144, v114
	s_waitcnt lgkmcnt(0)
	v_mul_f32_e32 v115, v144, v115
	v_mov_b32_e32 v114, v93
	v_pk_mul_f32 v[100:101], v[100:101], v[114:115]
	v_mul_f32_e32 v98, v99, v98
	v_mov_b32_e32 v93, v100
	v_mov_b32_e32 v99, v101
	v_pk_add_f32 v[92:93], v[92:93], v[98:99]
.LBB0_1027:
	v_cvt_pk_bf16_f32 v94, v94, v95
	v_cvt_pk_bf16_f32 v95, v96, v97
	v_cvt_pk_bf16_f32 v96, v90, v91
	v_mov_b64_e32 v[90:91], s[58:59]
	v_mad_i64_i32 v[90:91], s[2:3], v116, s57, v[90:91]
	v_cvt_pk_bf16_f32 v97, v92, v93
	v_lshl_add_u64 v[90:91], v[130:131], 1, v[90:91]
	global_store_dwordx4 v[90:91], v[94:97], off
	s_and_b64 vcc, exec, s[40:41]
	v_add_u32_e32 v108, 0x90, v171
	s_cbranch_vccnz .LBB0_1029
	v_cmp_gt_i32_e32 vcc, s89, v108
	v_and_b32_e32 v90, 0xfdf, v108
	v_lshlrev_b32_e32 v91, 2, v165
	v_cndmask_b32_e32 v90, v167, v90, vcc
	v_lshl_or_b32 v94, v90, 7, v91
	v_and_b32_e32 v91, 64, v248
	v_xor_b32_e32 v90, 32, v248
	v_add_u32_e32 v91, 64, v91
	v_cmp_lt_i32_e32 vcc, v90, v91
	s_nop 1
	v_cndmask_b32_e32 v90, v248, v90, vcc
	v_lshlrev_b32_e32 v109, 2, v90
	ds_bpermute_b32 v110, v109, v86
	ds_bpermute_b32 v111, v109, v87
	s_waitcnt lgkmcnt(0)
	v_pk_mul_f32 v[110:111], v[144:145], v[110:111]
	s_waitcnt vmcnt(1)
	v_mov_b64_e32 v[90:91], v[188:189]
	v_mov_b64_e32 v[92:93], v[190:191]
	v_mov_b64_e32 v[104:105], v[184:185]
	v_mov_b64_e32 v[106:107], v[186:187]
	v_mov_b64_e32 v[100:101], v[180:181]
	v_mov_b64_e32 v[102:103], v[182:183]
	v_mov_b64_e32 v[96:97], v[176:177]
	v_mov_b64_e32 v[98:99], v[178:179]
	v_add_u32_e32 v192, 0xa0, v171
	v_cmp_gt_i32_e32 vcc, s89, v192
	v_and_b32_e32 v192, 0xfef, v192
	v_lshlrev_b32_e32 v193, 2, v165
	v_cndmask_b32_e32 v192, v168, v192, vcc
	v_lshl_or_b32 v192, v192, 7, v193
	global_load_dwordx4 v[188:191], v192, s[0:1] offset:48
	global_load_dwordx4 v[184:187], v192, s[0:1] offset:32
	global_load_dwordx4 v[180:183], v192, s[0:1] offset:16
	global_load_dwordx4 v[176:179], v192, s[0:1]
	v_mov_b32_e32 v95, v98
	v_mov_b32_e32 v98, v97
	v_mov_b32_e32 v94, v96
	v_pk_mul_f32 v[96:97], v[98:99], v[110:111]
	ds_bpermute_b32 v110, v109, v88
	ds_bpermute_b32 v111, v109, v89
	v_mov_b32_e32 v99, v102
	v_mov_b32_e32 v102, v101
	v_mov_b32_e32 v98, v100
	v_pk_fma_f32 v[86:87], v[86:87], v[94:95], v[96:97]
	s_waitcnt lgkmcnt(0)
	v_pk_mul_f32 v[110:111], v[144:145], v[110:111]
	s_nop 0
	v_pk_mul_f32 v[100:101], v[102:103], v[110:111]
	ds_bpermute_b32 v110, v109, v82
	ds_bpermute_b32 v111, v109, v83
	v_mov_b32_e32 v103, v106
	v_mov_b32_e32 v106, v105
	v_mov_b32_e32 v102, v104
	v_pk_fma_f32 v[88:89], v[88:89], v[98:99], v[100:101]
	s_waitcnt lgkmcnt(0)
	v_pk_mul_f32 v[110:111], v[144:145], v[110:111]
	s_nop 0
	v_pk_mul_f32 v[104:105], v[106:107], v[110:111]
	ds_bpermute_b32 v106, v109, v84
	ds_bpermute_b32 v107, v109, v85
	v_mul_f32_e32 v84, v84, v90
	v_pk_fma_f32 v[82:83], v[82:83], v[102:103], v[104:105]
	s_waitcnt lgkmcnt(1)
	v_mul_f32_e32 v90, v144, v106
	s_waitcnt lgkmcnt(0)
	v_mul_f32_e32 v107, v144, v107
	v_mov_b32_e32 v106, v85
	v_pk_mul_f32 v[92:93], v[92:93], v[106:107]
	v_mul_f32_e32 v90, v91, v90
	v_mov_b32_e32 v85, v92
	v_mov_b32_e32 v91, v93
	v_pk_add_f32 v[84:85], v[84:85], v[90:91]
; __device__ __forceinline__ unsigned cvtpk(float lo, float hi) { f32x2_t v = {lo, hi}; bf16x2_t b = __builtin_convertvector(v, bf16x2_t); return __builtin_bit_cast(unsigned, b); }
;     __device__ __forceinline__ void operator()(const f32x4 (&acc)[2][2][4][2], const Unit& u, int wr, int wc, int fr, int fq) const {
;     ...
;                     const int r = EPI_ROW(u, ai, wr, m, fr);
;                     float v[8];
; #pragma unroll
;                     for (int e = 0; e < 4; ++e) { v[e] = acc[ai][bj][m][0][e]; v[4 + e] = acc[ai][bj][m][1][e]; }
;                     if (isrope) {
;                         const int pos = pos_of(r);
;                         const int i0 = (8 * fq) & 15;
;                         const float* rp = rope + ((size_t)pos * 16 + i0) * 2;
;                         const float sg = (fq < 2) ? -1.f : 1.f;
; #pragma unroll
;                         for (int e2 = 0; e2 < 4; ++e2) {
;                             const f32x4 t4 = *(const f32x4*)(rp + 4 * e2);
;                             const float pv0 = __shfl_xor(v[2 * e2], 32), pv1 = __shfl_xor(v[2 * e2 + 1], 32);
;                             v[2 * e2] = v[2 * e2] * t4[0] + sg * pv0 * t4[1];
;                             v[2 * e2 + 1] = v[2 * e2 + 1] * t4[2] + sg * pv1 * t4[3];
;                         }
;                     }
;                     u32x4 w; w.x = cvtpk(v[0], v[1]); w.y = cvtpk(v[2], v[3]); w.z = cvtpk(v[4], v[5]); w.w = cvtpk(v[6], v[7]);
;                     *(u32x4*)(QC + (size_t)r * 576 + c0) = w;
.LBB0_1029:
	v_cvt_pk_bf16_f32 v86, v86, v87
	v_cvt_pk_bf16_f32 v87, v88, v89
	v_cvt_pk_bf16_f32 v88, v82, v83
	v_mov_b64_e32 v[82:83], s[58:59]
	v_mad_i64_i32 v[82:83], s[2:3], v108, s57, v[82:83]
	v_cvt_pk_bf16_f32 v89, v84, v85
	v_lshl_add_u64 v[82:83], v[130:131], 1, v[82:83]
	global_store_dwordx4 v[82:83], v[86:89], off
	s_and_b64 vcc, exec, s[40:41]
	v_add_u32_e32 v100, 0xa0, v171
	s_cbranch_vccnz .LBB0_1031
	v_cmp_gt_i32_e32 vcc, s89, v100
	v_and_b32_e32 v82, 0xfef, v100
	v_lshlrev_b32_e32 v83, 2, v165
	v_cndmask_b32_e32 v82, v168, v82, vcc
	v_lshl_or_b32 v86, v82, 7, v83
	v_and_b32_e32 v83, 64, v248
	v_xor_b32_e32 v82, 32, v248
	v_add_u32_e32 v83, 64, v83
	v_cmp_lt_i32_e32 vcc, v82, v83
	s_nop 1
	v_cndmask_b32_e32 v82, v248, v82, vcc
	v_lshlrev_b32_e32 v101, 2, v82
	ds_bpermute_b32 v102, v101, v78
	ds_bpermute_b32 v103, v101, v79
	s_waitcnt lgkmcnt(0)
	v_pk_mul_f32 v[102:103], v[144:145], v[102:103]
	s_waitcnt vmcnt(1)
	v_mov_b64_e32 v[82:83], v[188:189]
	v_mov_b64_e32 v[84:85], v[190:191]
	v_mov_b64_e32 v[96:97], v[184:185]
	v_mov_b64_e32 v[98:99], v[186:187]
	v_mov_b64_e32 v[92:93], v[180:181]
	v_mov_b64_e32 v[94:95], v[182:183]
	v_mov_b64_e32 v[88:89], v[176:177]
	v_mov_b64_e32 v[90:91], v[178:179]
	v_add_u32_e32 v192, 0xb0, v171
	v_cmp_gt_i32_e32 vcc, s89, v192
	v_and_b32_e32 v192, 0xfff, v192
	v_lshlrev_b32_e32 v193, 2, v165
	v_cndmask_b32_e32 v192, v169, v192, vcc
	v_lshl_or_b32 v192, v192, 7, v193
	global_load_dwordx4 v[188:191], v192, s[0:1] offset:48
	global_load_dwordx4 v[184:187], v192, s[0:1] offset:32
	global_load_dwordx4 v[180:183], v192, s[0:1] offset:16
	global_load_dwordx4 v[176:179], v192, s[0:1]
	v_mov_b32_e32 v87, v90
	v_mov_b32_e32 v90, v89
	v_mov_b32_e32 v86, v88
	v_pk_mul_f32 v[88:89], v[90:91], v[102:103]
	ds_bpermute_b32 v102, v101, v80
	ds_bpermute_b32 v103, v101, v81
	v_mov_b32_e32 v91, v94
	v_mov_b32_e32 v94, v93
	v_mov_b32_e32 v90, v92
	v_pk_fma_f32 v[78:79], v[78:79], v[86:87], v[88:89]
	s_waitcnt lgkmcnt(0)
	v_pk_mul_f32 v[102:103], v[144:145], v[102:103]
	s_nop 0
	v_pk_mul_f32 v[92:93], v[94:95], v[102:103]
	ds_bpermute_b32 v102, v101, v74
	ds_bpermute_b32 v103, v101, v75
	v_mov_b32_e32 v95, v98
	v_mov_b32_e32 v98, v97
	v_mov_b32_e32 v94, v96
	v_pk_fma_f32 v[80:81], v[80:81], v[90:91], v[92:93]
	s_waitcnt lgkmcnt(0)
	v_pk_mul_f32 v[102:103], v[144:145], v[102:103]
	s_nop 0
	v_pk_mul_f32 v[96:97], v[98:99], v[102:103]
	ds_bpermute_b32 v98, v101, v76
	ds_bpermute_b32 v99, v101, v77
	v_mul_f32_e32 v76, v76, v82
	v_pk_fma_f32 v[74:75], v[74:75], v[94:95], v[96:97]
	s_waitcnt lgkmcnt(1)
	v_mul_f32_e32 v82, v144, v98
	s_waitcnt lgkmcnt(0)
	v_mul_f32_e32 v99, v144, v99
	v_mov_b32_e32 v98, v77
	v_pk_mul_f32 v[84:85], v[84:85], v[98:99]
	v_mul_f32_e32 v82, v83, v82
	v_mov_b32_e32 v77, v84
	v_mov_b32_e32 v83, v85
	v_pk_add_f32 v[76:77], v[76:77], v[82:83]
.LBB0_1031:
	v_cvt_pk_bf16_f32 v78, v78, v79
	v_cvt_pk_bf16_f32 v79, v80, v81
	v_cvt_pk_bf16_f32 v80, v74, v75
	v_mov_b64_e32 v[74:75], s[58:59]
	v_mad_i64_i32 v[74:75], s[2:3], v100, s57, v[74:75]
	v_cvt_pk_bf16_f32 v81, v76, v77
	v_lshl_add_u64 v[74:75], v[130:131], 1, v[74:75]
	global_store_dwordx4 v[74:75], v[78:81], off
	s_and_b64 vcc, exec, s[40:41]
	v_add_u32_e32 v92, 0xb0, v171
	s_cbranch_vccnz .LBB0_1033
	v_cmp_gt_i32_e32 vcc, s89, v92
	v_and_b32_e32 v74, 0xfff, v92
	v_lshlrev_b32_e32 v75, 2, v165
	v_cndmask_b32_e32 v74, v169, v74, vcc
	v_lshl_or_b32 v78, v74, 7, v75
	v_and_b32_e32 v75, 64, v248
	v_xor_b32_e32 v74, 32, v248
	v_add_u32_e32 v75, 64, v75
	v_cmp_lt_i32_e32 vcc, v74, v75
	s_nop 1
	v_cndmask_b32_e32 v74, v248, v74, vcc
	v_lshlrev_b32_e32 v93, 2, v74
	ds_bpermute_b32 v94, v93, v70
	ds_bpermute_b32 v95, v93, v71
	s_waitcnt lgkmcnt(0)
	v_pk_mul_f32 v[94:95], v[144:145], v[94:95]
	s_waitcnt vmcnt(1)
	v_mov_b64_e32 v[74:75], v[188:189]
	v_mov_b64_e32 v[76:77], v[190:191]
	v_mov_b64_e32 v[88:89], v[184:185]
	v_mov_b64_e32 v[90:91], v[186:187]
	v_mov_b64_e32 v[84:85], v[180:181]
	v_mov_b64_e32 v[86:87], v[182:183]
	v_mov_b64_e32 v[80:81], v[176:177]
	v_mov_b64_e32 v[82:83], v[178:179]
	v_mov_b32_e32 v79, v82
	v_mov_b32_e32 v82, v81
	v_mov_b32_e32 v78, v80
	v_pk_mul_f32 v[80:81], v[82:83], v[94:95]
	ds_bpermute_b32 v94, v93, v72
	ds_bpermute_b32 v95, v93, v73
	v_mov_b32_e32 v83, v86
	v_mov_b32_e32 v86, v85
	v_mov_b32_e32 v82, v84
	v_pk_fma_f32 v[70:71], v[70:71], v[78:79], v[80:81]
	s_waitcnt lgkmcnt(0)
	v_pk_mul_f32 v[94:95], v[144:145], v[94:95]
	s_nop 0
	v_pk_mul_f32 v[84:85], v[86:87], v[94:95]
	ds_bpermute_b32 v94, v93, v66
	ds_bpermute_b32 v95, v93, v67
	v_mov_b32_e32 v87, v90
	v_mov_b32_e32 v90, v89
	v_mov_b32_e32 v86, v88
	v_pk_fma_f32 v[72:73], v[72:73], v[82:83], v[84:85]
	s_waitcnt lgkmcnt(0)
	v_pk_mul_f32 v[94:95], v[144:145], v[94:95]
	s_nop 0
	v_pk_mul_f32 v[88:89], v[90:91], v[94:95]
	ds_bpermute_b32 v90, v93, v68
	ds_bpermute_b32 v91, v93, v69
	v_mul_f32_e32 v68, v68, v74
	v_pk_fma_f32 v[66:67], v[66:67], v[86:87], v[88:89]
	s_waitcnt lgkmcnt(1)
	v_mul_f32_e32 v74, v144, v90
	s_waitcnt lgkmcnt(0)
	v_mul_f32_e32 v91, v144, v91
	v_mov_b32_e32 v90, v69
	v_pk_mul_f32 v[76:77], v[76:77], v[90:91]
	v_mul_f32_e32 v74, v75, v74
	v_mov_b32_e32 v69, v76
	v_mov_b32_e32 v75, v77
	v_pk_add_f32 v[68:69], v[68:69], v[74:75]

; __device__ __forceinline__ unsigned cvtpk(float lo, float hi) { f32x2_t v = {lo, hi}; bf16x2_t b = __builtin_convertvector(v, bf16x2_t); return __builtin_bit_cast(unsigned, b); }
;     __device__ __forceinline__ void operator()(const f32x4 (&acc)[2][2][4][2], const Unit& u, int wr, int wc, int fr, int fq) const {
;     ...
;                     const int r = EPI_ROW(u, ai, wr, m, fr);
;                     float v[8];
; #pragma unroll
;                     for (int e = 0; e < 4; ++e) { v[e] = acc[ai][bj][m][0][e]; v[4 + e] = acc[ai][bj][m][1][e]; }
;                     if (isrope) {
;                         const int pos = pos_of(r);
;                         const int i0 = (8 * fq) & 15;
;                         const float* rp = rope + ((size_t)pos * 16 + i0) * 2;
;                         const float sg = (fq < 2) ? -1.f : 1.f;
; #pragma unroll
;                         for (int e2 = 0; e2 < 4; ++e2) {
;                             const f32x4 t4 = *(const f32x4*)(rp + 4 * e2);
;                             const float pv0 = __shfl_xor(v[2 * e2], 32), pv1 = __shfl_xor(v[2 * e2 + 1], 32);
;                             v[2 * e2] = v[2 * e2] * t4[0] + sg * pv0 * t4[1];
;                             v[2 * e2 + 1] = v[2 * e2 + 1] * t4[2] + sg * pv1 * t4[3];
;                         }
;                     }
;                     u32x4 w; w.x = cvtpk(v[0], v[1]); w.y = cvtpk(v[2], v[3]); w.z = cvtpk(v[4], v[5]); w.w = cvtpk(v[6], v[7]);
;                     *(u32x4*)(QC + (size_t)r * 576 + c0) = w;
.LBB0_1036:
	s_mul_hi_i32 s3, s2, 0x2aaaaaab
	s_lshr_b32 s8, s3, 31
	s_lshr_b32 s3, s3, 4
	s_add_i32 s3, s3, s8
	s_mulk_i32 s3, 0x60
	s_sub_i32 s8, s2, s3
	s_cmp_eq_u32 s8, 64
	s_cselect_b64 s[2:3], -1, 0
	s_cmp_lg_u32 s8, 64
	v_lshlrev_b32_e32 v84, 2, v165
	s_cbranch_scc1 .LBB0_1038
	v_cmp_gt_i32_e32 vcc, s89, v171
	v_and_b32_e32 v66, 0xfcf, v171
	v_and_b32_e32 v67, 64, v248
	v_cndmask_b32_e32 v66, v166, v66, vcc
	v_lshl_or_b32 v70, v66, 7, v84
	v_xor_b32_e32 v66, 32, v248
	v_add_u32_e32 v67, 64, v67
	v_cmp_lt_i32_e32 vcc, v66, v67
	s_nop 1
	v_cndmask_b32_e32 v66, v248, v66, vcc
	v_lshlrev_b32_e32 v85, 2, v66
	global_load_dwordx4 v[66:69], v70, s[0:1] offset:48
	global_load_dwordx4 v[80:83], v70, s[0:1] offset:32
	global_load_dwordx4 v[76:79], v70, s[0:1] offset:16
	global_load_dwordx4 v[72:75], v70, s[0:1]
	v_or_b32_e32 v192, 16, v171
	v_cmp_gt_i32_e32 vcc, s89, v192
	v_and_b32_e32 v192, 0xfdf, v192
	v_lshlrev_b32_e32 v193, 2, v165
	v_cndmask_b32_e32 v192, v167, v192, vcc
	v_lshl_or_b32 v192, v192, 7, v193
	global_load_dwordx4 v[188:191], v192, s[0:1] offset:48
	global_load_dwordx4 v[184:187], v192, s[0:1] offset:32
	global_load_dwordx4 v[180:183], v192, s[0:1] offset:16
	global_load_dwordx4 v[176:179], v192, s[0:1]
	ds_bpermute_b32 v86, v85, v62
	ds_bpermute_b32 v87, v85, v63
	s_waitcnt lgkmcnt(0)
	v_pk_mul_f32 v[86:87], v[144:145], v[86:87]
	s_waitcnt vmcnt(4)
	v_mov_b32_e32 v71, v74
	v_mov_b32_e32 v74, v73
	v_mov_b32_e32 v70, v72
	v_pk_mul_f32 v[72:73], v[74:75], v[86:87]
	ds_bpermute_b32 v86, v85, v64
	ds_bpermute_b32 v87, v85, v65
	v_mov_b32_e32 v75, v78
	v_mov_b32_e32 v78, v77
	v_mov_b32_e32 v74, v76
	v_pk_fma_f32 v[62:63], v[62:63], v[70:71], v[72:73]
	s_waitcnt lgkmcnt(0)
	v_pk_mul_f32 v[86:87], v[144:145], v[86:87]
	s_nop 0
	v_pk_mul_f32 v[76:77], v[78:79], v[86:87]
	ds_bpermute_b32 v86, v85, v58
	ds_bpermute_b32 v87, v85, v59
	v_mov_b32_e32 v79, v82
	v_mov_b32_e32 v82, v81
	v_mov_b32_e32 v78, v80
	v_pk_fma_f32 v[64:65], v[64:65], v[74:75], v[76:77]
	s_waitcnt lgkmcnt(0)
	v_pk_mul_f32 v[86:87], v[144:145], v[86:87]
	s_nop 0
	v_pk_mul_f32 v[80:81], v[82:83], v[86:87]
	ds_bpermute_b32 v82, v85, v60
	ds_bpermute_b32 v83, v85, v61
	v_mul_f32_e32 v60, v60, v66
	v_pk_fma_f32 v[58:59], v[58:59], v[78:79], v[80:81]
	s_waitcnt lgkmcnt(1)
	v_mul_f32_e32 v66, v144, v82
	s_waitcnt lgkmcnt(0)
	v_mul_f32_e32 v83, v144, v83
	v_mov_b32_e32 v82, v61
	v_pk_mul_f32 v[68:69], v[68:69], v[82:83]
	v_mul_f32_e32 v66, v67, v66
	v_mov_b32_e32 v61, v68
	v_mov_b32_e32 v67, v69
	v_pk_add_f32 v[60:61], v[60:61], v[66:67]
.LBB0_1038:
	v_cvt_pk_bf16_f32 v68, v58, v59
	v_mov_b64_e32 v[58:59], s[58:59]
	s_ashr_i32 s23, s22, 31
	v_cvt_pk_bf16_f32 v66, v62, v63
	v_mad_i64_i32 v[58:59], s[36:37], v171, s57, v[58:59]
	v_lshl_add_u64 v[62:63], s[22:23], 0, v[142:143]
	v_cvt_pk_bf16_f32 v67, v64, v65
	v_cvt_pk_bf16_f32 v69, v60, v61
	v_lshl_add_u64 v[58:59], v[62:63], 1, v[58:59]
	global_store_dwordx4 v[58:59], v[66:69], off offset:256
	v_cndmask_b32_e64 v58, 0, 1, s[2:3]
	v_cmp_ne_u32_e64 s[40:41], 1, v58
	s_andn2_b64 vcc, exec, s[2:3]
	v_or_b32_e32 v78, 16, v171
	s_cbranch_vccnz .LBB0_1040
	v_cmp_gt_i32_e32 vcc, s89, v78
	v_and_b32_e32 v58, 0xfdf, v78
	v_and_b32_e32 v59, 64, v248
	v_cndmask_b32_e32 v58, v167, v58, vcc
	v_lshl_or_b32 v64, v58, 7, v84
	v_xor_b32_e32 v58, 32, v248
	v_add_u32_e32 v59, 64, v59
	v_cmp_lt_i32_e32 vcc, v58, v59
	s_nop 1
	v_cndmask_b32_e32 v58, v248, v58, vcc
	v_lshlrev_b32_e32 v79, 2, v58
	ds_bpermute_b32 v80, v79, v54
	ds_bpermute_b32 v81, v79, v55
	s_waitcnt lgkmcnt(0)
	v_pk_mul_f32 v[80:81], v[144:145], v[80:81]
	s_waitcnt vmcnt(1)
	v_mov_b64_e32 v[58:59], v[188:189]
	v_mov_b64_e32 v[60:61], v[190:191]
	v_mov_b64_e32 v[74:75], v[184:185]
	v_mov_b64_e32 v[76:77], v[186:187]
	v_mov_b64_e32 v[70:71], v[180:181]
	v_mov_b64_e32 v[72:73], v[182:183]
	v_mov_b64_e32 v[66:67], v[176:177]
	v_mov_b64_e32 v[68:69], v[178:179]
	v_or_b32_e32 v192, 32, v171
	v_cmp_gt_i32_e32 vcc, s89, v192
	v_and_b32_e32 v192, 0xfef, v192
	v_lshlrev_b32_e32 v193, 2, v165
	v_cndmask_b32_e32 v192, v168, v192, vcc
	v_lshl_or_b32 v192, v192, 7, v193
	global_load_dwordx4 v[188:191], v192, s[0:1] offset:48
	global_load_dwordx4 v[184:187], v192, s[0:1] offset:32
	global_load_dwordx4 v[180:183], v192, s[0:1] offset:16
	global_load_dwordx4 v[176:179], v192, s[0:1]
	v_mov_b32_e32 v65, v68
	v_mov_b32_e32 v68, v67
	v_mov_b32_e32 v64, v66
	v_pk_mul_f32 v[66:67], v[68:69], v[80:81]
	ds_bpermute_b32 v80, v79, v56
	ds_bpermute_b32 v81, v79, v57
	v_mov_b32_e32 v69, v72
	v_mov_b32_e32 v72, v71
	v_mov_b32_e32 v68, v70
	v_pk_fma_f32 v[54:55], v[54:55], v[64:65], v[66:67]
	s_waitcnt lgkmcnt(0)
	v_pk_mul_f32 v[80:81], v[144:145], v[80:81]
	s_nop 0
	v_pk_mul_f32 v[70:71], v[72:73], v[80:81]
	ds_bpermute_b32 v80, v79, v50
	ds_bpermute_b32 v81, v79, v51
	v_mov_b32_e32 v73, v76
	v_mov_b32_e32 v76, v75
	v_mov_b32_e32 v72, v74
	v_pk_fma_f32 v[56:57], v[56:57], v[68:69], v[70:71]
	s_waitcnt lgkmcnt(0)
	v_pk_mul_f32 v[80:81], v[144:145], v[80:81]
	s_nop 0
	v_pk_mul_f32 v[74:75], v[76:77], v[80:81]
	ds_bpermute_b32 v76, v79, v52
	ds_bpermute_b32 v77, v79, v53
	v_mul_f32_e32 v52, v52, v58
	v_pk_fma_f32 v[50:51], v[50:51], v[72:73], v[74:75]
	s_waitcnt lgkmcnt(1)
	v_mul_f32_e32 v58, v144, v76
	s_waitcnt lgkmcnt(0)
	v_mul_f32_e32 v77, v144, v77
	v_mov_b32_e32 v76, v53
	v_pk_mul_f32 v[60:61], v[60:61], v[76:77]
	v_mul_f32_e32 v58, v59, v58
	v_mov_b32_e32 v53, v60
	v_mov_b32_e32 v59, v61
	v_pk_add_f32 v[52:53], v[52:53], v[58:59]
; __device__ __forceinline__ unsigned cvtpk(float lo, float hi) { f32x2_t v = {lo, hi}; bf16x2_t b = __builtin_convertvector(v, bf16x2_t); return __builtin_bit_cast(unsigned, b); }
;     __device__ __forceinline__ void operator()(const f32x4 (&acc)[2][2][4][2], const Unit& u, int wr, int wc, int fr, int fq) const {
;     ...
;                     const int r = EPI_ROW(u, ai, wr, m, fr);
;                     float v[8];
; #pragma unroll
;                     for (int e = 0; e < 4; ++e) { v[e] = acc[ai][bj][m][0][e]; v[4 + e] = acc[ai][bj][m][1][e]; }
;                     if (isrope) {
;                         const int pos = pos_of(r);
;                         const int i0 = (8 * fq) & 15;
;                         const float* rp = rope + ((size_t)pos * 16 + i0) * 2;
;                         const float sg = (fq < 2) ? -1.f : 1.f;
; #pragma unroll
;                         for (int e2 = 0; e2 < 4; ++e2) {
;                             const f32x4 t4 = *(const f32x4*)(rp + 4 * e2);
;                             const float pv0 = __shfl_xor(v[2 * e2], 32), pv1 = __shfl_xor(v[2 * e2 + 1], 32);
;                             v[2 * e2] = v[2 * e2] * t4[0] + sg * pv0 * t4[1];
;                             v[2 * e2 + 1] = v[2 * e2 + 1] * t4[2] + sg * pv1 * t4[3];
;                         }
;                     }
;                     u32x4 w; w.x = cvtpk(v[0], v[1]); w.y = cvtpk(v[2], v[3]); w.z = cvtpk(v[4], v[5]); w.w = cvtpk(v[6], v[7]);
;                     *(u32x4*)(QC + (size_t)r * 576 + c0) = w;
.LBB0_1040:
	v_cvt_pk_bf16_f32 v54, v54, v55
	v_cvt_pk_bf16_f32 v55, v56, v57
	v_cvt_pk_bf16_f32 v56, v50, v51
	v_mov_b64_e32 v[50:51], s[58:59]
	v_mad_i64_i32 v[50:51], s[2:3], v78, s57, v[50:51]
	v_cvt_pk_bf16_f32 v57, v52, v53
	v_lshl_add_u64 v[50:51], v[62:63], 1, v[50:51]
	global_store_dwordx4 v[50:51], v[54:57], off offset:256
	s_and_b64 vcc, exec, s[40:41]
	v_or_b32_e32 v70, 32, v171
	s_cbranch_vccnz .LBB0_1042
	v_cmp_gt_i32_e32 vcc, s89, v70
	v_and_b32_e32 v50, 0xfef, v70
	v_and_b32_e32 v51, 64, v248
	v_cndmask_b32_e32 v50, v168, v50, vcc
	v_lshl_or_b32 v54, v50, 7, v84
	v_xor_b32_e32 v50, 32, v248
	v_add_u32_e32 v51, 64, v51
	v_cmp_lt_i32_e32 vcc, v50, v51
	s_nop 1
	v_cndmask_b32_e32 v50, v248, v50, vcc
	v_lshlrev_b32_e32 v71, 2, v50
	ds_bpermute_b32 v60, v71, v46
	ds_bpermute_b32 v61, v71, v47
	s_waitcnt lgkmcnt(0)
	v_pk_mul_f32 v[60:61], v[144:145], v[60:61]
	s_waitcnt vmcnt(1)
	v_mov_b64_e32 v[50:51], v[188:189]
	v_mov_b64_e32 v[52:53], v[190:191]
	v_mov_b64_e32 v[66:67], v[184:185]
	v_mov_b64_e32 v[68:69], v[186:187]
	v_mov_b64_e32 v[72:73], v[180:181]
	v_mov_b64_e32 v[74:75], v[182:183]
	v_mov_b64_e32 v[56:57], v[176:177]
	v_mov_b64_e32 v[58:59], v[178:179]
	v_or_b32_e32 v192, 48, v171
	v_cmp_gt_i32_e32 vcc, s89, v192
	v_and_b32_e32 v192, 0xfff, v192
	v_lshlrev_b32_e32 v193, 2, v165
	v_cndmask_b32_e32 v192, v169, v192, vcc
	v_lshl_or_b32 v192, v192, 7, v193
	global_load_dwordx4 v[188:191], v192, s[0:1] offset:48
	global_load_dwordx4 v[184:187], v192, s[0:1] offset:32
	global_load_dwordx4 v[180:183], v192, s[0:1] offset:16
	global_load_dwordx4 v[176:179], v192, s[0:1]
	v_mov_b32_e32 v65, v68
	v_mov_b32_e32 v68, v67
	v_mov_b32_e32 v55, v58
	v_mov_b32_e32 v58, v57
	v_mov_b32_e32 v54, v56
	v_pk_mul_f32 v[56:57], v[58:59], v[60:61]
	v_mov_b32_e32 v58, v72
	v_mov_b32_e32 v59, v74
	v_mov_b32_e32 v74, v73
	ds_bpermute_b32 v72, v71, v42
	ds_bpermute_b32 v73, v71, v43
	v_mov_b32_e32 v64, v66
	ds_bpermute_b32 v60, v71, v48
	ds_bpermute_b32 v61, v71, v49
	v_pk_fma_f32 v[46:47], v[46:47], v[54:55], v[56:57]
	s_waitcnt lgkmcnt(2)
	v_pk_mul_f32 v[72:73], v[144:145], v[72:73]
	s_waitcnt lgkmcnt(0)
	v_pk_mul_f32 v[60:61], v[144:145], v[60:61]
	v_pk_mul_f32 v[66:67], v[68:69], v[72:73]
	ds_bpermute_b32 v68, v71, v44
	ds_bpermute_b32 v69, v71, v45
	v_mul_f32_e32 v44, v44, v50
	v_pk_mul_f32 v[60:61], v[74:75], v[60:61]
	v_pk_fma_f32 v[42:43], v[42:43], v[64:65], v[66:67]
	s_waitcnt lgkmcnt(1)
	v_mul_f32_e32 v50, v144, v68
	s_waitcnt lgkmcnt(0)
	v_mul_f32_e32 v69, v144, v69
	v_mov_b32_e32 v68, v45
	v_pk_mul_f32 v[52:53], v[52:53], v[68:69]
	v_mul_f32_e32 v50, v51, v50
	v_mov_b32_e32 v45, v52
	v_mov_b32_e32 v51, v53
	v_pk_fma_f32 v[48:49], v[48:49], v[58:59], v[60:61]
	v_pk_add_f32 v[44:45], v[44:45], v[50:51]
.LBB0_1042:
	v_cvt_pk_bf16_f32 v46, v46, v47
	v_cvt_pk_bf16_f32 v47, v48, v49
	v_cvt_pk_bf16_f32 v48, v42, v43
	v_mov_b64_e32 v[42:43], s[58:59]
	v_mad_i64_i32 v[42:43], s[2:3], v70, s57, v[42:43]
	v_cvt_pk_bf16_f32 v49, v44, v45
	v_lshl_add_u64 v[42:43], v[62:63], 1, v[42:43]
	global_store_dwordx4 v[42:43], v[46:49], off offset:256
	s_and_b64 vcc, exec, s[40:41]
	v_or_b32_e32 v60, 48, v171
	s_cbranch_vccnz .LBB0_1044
	v_cmp_gt_i32_e32 vcc, s89, v60
	v_and_b32_e32 v42, 0xfff, v60
	v_and_b32_e32 v43, 64, v248
	v_cndmask_b32_e32 v42, v169, v42, vcc
	v_lshl_or_b32 v46, v42, 7, v84
	v_xor_b32_e32 v42, 32, v248
	v_add_u32_e32 v43, 64, v43
	v_cmp_lt_i32_e32 vcc, v42, v43
	s_nop 1
	v_cndmask_b32_e32 v42, v248, v42, vcc
	v_lshlrev_b32_e32 v61, 2, v42
	ds_bpermute_b32 v64, v61, v38
	ds_bpermute_b32 v65, v61, v39
	s_waitcnt lgkmcnt(0)
	v_pk_mul_f32 v[64:65], v[144:145], v[64:65]
	s_waitcnt vmcnt(1)
	v_mov_b64_e32 v[42:43], v[188:189]
	v_mov_b64_e32 v[44:45], v[190:191]
	v_mov_b64_e32 v[56:57], v[184:185]
	v_mov_b64_e32 v[58:59], v[186:187]
	v_mov_b64_e32 v[52:53], v[180:181]
	v_mov_b64_e32 v[54:55], v[182:183]
	v_mov_b64_e32 v[48:49], v[176:177]
	v_mov_b64_e32 v[50:51], v[178:179]
	v_add_u32_e32 v192, 0x80, v171
	v_cmp_gt_i32_e32 vcc, s89, v192
	v_and_b32_e32 v192, 0xfcf, v192
	v_lshlrev_b32_e32 v193, 2, v165
	v_cndmask_b32_e32 v192, v166, v192, vcc
	v_lshl_or_b32 v192, v192, 7, v193
	global_load_dwordx4 v[188:191], v192, s[0:1] offset:48
	global_load_dwordx4 v[184:187], v192, s[0:1] offset:32
	global_load_dwordx4 v[180:183], v192, s[0:1] offset:16
	global_load_dwordx4 v[176:179], v192, s[0:1]
	v_mov_b32_e32 v47, v50
	v_mov_b32_e32 v50, v49
	v_mov_b32_e32 v46, v48
	v_pk_mul_f32 v[48:49], v[50:51], v[64:65]
	ds_bpermute_b32 v64, v61, v40
	ds_bpermute_b32 v65, v61, v41
	v_mov_b32_e32 v51, v54
	v_mov_b32_e32 v54, v53
	v_mov_b32_e32 v50, v52
	v_pk_fma_f32 v[38:39], v[38:39], v[46:47], v[48:49]
	s_waitcnt lgkmcnt(0)
	v_pk_mul_f32 v[64:65], v[144:145], v[64:65]
	s_nop 0
	v_pk_mul_f32 v[52:53], v[54:55], v[64:65]
	ds_bpermute_b32 v64, v61, v34
	ds_bpermute_b32 v65, v61, v35
	v_mov_b32_e32 v55, v58
	v_mov_b32_e32 v58, v57
	v_mov_b32_e32 v54, v56
	v_pk_fma_f32 v[40:41], v[40:41], v[50:51], v[52:53]
	s_waitcnt lgkmcnt(0)
	v_pk_mul_f32 v[64:65], v[144:145], v[64:65]
	s_nop 0
	v_pk_mul_f32 v[56:57], v[58:59], v[64:65]
	ds_bpermute_b32 v58, v61, v36
	ds_bpermute_b32 v59, v61, v37
	v_mul_f32_e32 v36, v36, v42
	v_pk_fma_f32 v[34:35], v[34:35], v[54:55], v[56:57]
	s_waitcnt lgkmcnt(1)
	v_mul_f32_e32 v42, v144, v58
	s_waitcnt lgkmcnt(0)
	v_mul_f32_e32 v59, v144, v59
	v_mov_b32_e32 v58, v37
	v_pk_mul_f32 v[44:45], v[44:45], v[58:59]
	v_mul_f32_e32 v42, v43, v42
	v_mov_b32_e32 v37, v44
	v_mov_b32_e32 v43, v45
	v_pk_add_f32 v[36:37], v[36:37], v[42:43]
; __device__ __forceinline__ unsigned cvtpk(float lo, float hi) { f32x2_t v = {lo, hi}; bf16x2_t b = __builtin_convertvector(v, bf16x2_t); return __builtin_bit_cast(unsigned, b); }
;     __device__ __forceinline__ void operator()(const f32x4 (&acc)[2][2][4][2], const Unit& u, int wr, int wc, int fr, int fq) const {
;     ...
;                     const int r = EPI_ROW(u, ai, wr, m, fr);
;                     float v[8];
; #pragma unroll
;                     for (int e = 0; e < 4; ++e) { v[e] = acc[ai][bj][m][0][e]; v[4 + e] = acc[ai][bj][m][1][e]; }
;                     if (isrope) {
;                         const int pos = pos_of(r);
;                         const int i0 = (8 * fq) & 15;
;                         const float* rp = rope + ((size_t)pos * 16 + i0) * 2;
;                         const float sg = (fq < 2) ? -1.f : 1.f;
; #pragma unroll
;                         for (int e2 = 0; e2 < 4; ++e2) {
;                             const f32x4 t4 = *(const f32x4*)(rp + 4 * e2);
;                             const float pv0 = __shfl_xor(v[2 * e2], 32), pv1 = __shfl_xor(v[2 * e2 + 1], 32);
;                             v[2 * e2] = v[2 * e2] * t4[0] + sg * pv0 * t4[1];
;                             v[2 * e2 + 1] = v[2 * e2 + 1] * t4[2] + sg * pv1 * t4[3];
;                         }
;                     }
;                     u32x4 w; w.x = cvtpk(v[0], v[1]); w.y = cvtpk(v[2], v[3]); w.z = cvtpk(v[4], v[5]); w.w = cvtpk(v[6], v[7]);
;                     *(u32x4*)(QC + (size_t)r * 576 + c0) = w;
.LBB0_1044:
	v_cvt_pk_bf16_f32 v38, v38, v39
	v_cvt_pk_bf16_f32 v39, v40, v41
	v_cvt_pk_bf16_f32 v40, v34, v35
	v_mov_b64_e32 v[34:35], s[58:59]
	v_mad_i64_i32 v[34:35], s[2:3], v60, s57, v[34:35]
	v_cvt_pk_bf16_f32 v41, v36, v37
	v_lshl_add_u64 v[34:35], v[62:63], 1, v[34:35]
	global_store_dwordx4 v[34:35], v[38:41], off offset:256
	s_and_b64 vcc, exec, s[40:41]
	v_add_u32_e32 v52, 0x80, v171
	s_cbranch_vccnz .LBB0_1046
	v_cmp_gt_i32_e32 vcc, s89, v52
	v_and_b32_e32 v34, 0xfcf, v52
	v_and_b32_e32 v35, 64, v248
	v_cndmask_b32_e32 v34, v166, v34, vcc
	v_lshl_or_b32 v38, v34, 7, v84
	v_xor_b32_e32 v34, 32, v248
	v_add_u32_e32 v35, 64, v35
	v_cmp_lt_i32_e32 vcc, v34, v35
	s_nop 1
	v_cndmask_b32_e32 v34, v248, v34, vcc
	v_lshlrev_b32_e32 v53, 2, v34
	ds_bpermute_b32 v54, v53, v30
	ds_bpermute_b32 v55, v53, v31
	s_waitcnt lgkmcnt(0)
	v_pk_mul_f32 v[54:55], v[144:145], v[54:55]
	s_waitcnt vmcnt(1)
	v_mov_b64_e32 v[34:35], v[188:189]
	v_mov_b64_e32 v[36:37], v[190:191]
	v_mov_b64_e32 v[48:49], v[184:185]
	v_mov_b64_e32 v[50:51], v[186:187]
	v_mov_b64_e32 v[44:45], v[180:181]
	v_mov_b64_e32 v[46:47], v[182:183]
	v_mov_b64_e32 v[40:41], v[176:177]
	v_mov_b64_e32 v[42:43], v[178:179]
	v_add_u32_e32 v192, 0x90, v171
	v_cmp_gt_i32_e32 vcc, s89, v192
	v_and_b32_e32 v192, 0xfdf, v192
	v_lshlrev_b32_e32 v193, 2, v165
	v_cndmask_b32_e32 v192, v167, v192, vcc
	v_lshl_or_b32 v192, v192, 7, v193
	global_load_dwordx4 v[188:191], v192, s[0:1] offset:48
	global_load_dwordx4 v[184:187], v192, s[0:1] offset:32
	global_load_dwordx4 v[180:183], v192, s[0:1] offset:16
	global_load_dwordx4 v[176:179], v192, s[0:1]
	v_mov_b32_e32 v39, v42
	v_mov_b32_e32 v42, v41
	v_mov_b32_e32 v38, v40
	v_pk_mul_f32 v[40:41], v[42:43], v[54:55]
	ds_bpermute_b32 v54, v53, v32
	ds_bpermute_b32 v55, v53, v33
	v_mov_b32_e32 v43, v46
	v_mov_b32_e32 v46, v45
	v_mov_b32_e32 v42, v44
	v_pk_fma_f32 v[30:31], v[30:31], v[38:39], v[40:41]
	s_waitcnt lgkmcnt(0)
	v_pk_mul_f32 v[54:55], v[144:145], v[54:55]
	s_nop 0
	v_pk_mul_f32 v[44:45], v[46:47], v[54:55]
	ds_bpermute_b32 v54, v53, v26
	ds_bpermute_b32 v55, v53, v27
	v_mov_b32_e32 v47, v50
	v_mov_b32_e32 v50, v49
	v_mov_b32_e32 v46, v48
	v_pk_fma_f32 v[32:33], v[32:33], v[42:43], v[44:45]
	s_waitcnt lgkmcnt(0)
	v_pk_mul_f32 v[54:55], v[144:145], v[54:55]
	s_nop 0
	v_pk_mul_f32 v[48:49], v[50:51], v[54:55]
	ds_bpermute_b32 v50, v53, v28
	ds_bpermute_b32 v51, v53, v29
	v_mul_f32_e32 v28, v28, v34
	v_pk_fma_f32 v[26:27], v[26:27], v[46:47], v[48:49]
	s_waitcnt lgkmcnt(1)
	v_mul_f32_e32 v34, v144, v50
	s_waitcnt lgkmcnt(0)
	v_mul_f32_e32 v51, v144, v51
	v_mov_b32_e32 v50, v29
	v_pk_mul_f32 v[36:37], v[36:37], v[50:51]
	v_mul_f32_e32 v34, v35, v34
	v_mov_b32_e32 v29, v36
	v_mov_b32_e32 v35, v37
	v_pk_add_f32 v[28:29], v[28:29], v[34:35]
.LBB0_1046:
	v_cvt_pk_bf16_f32 v30, v30, v31
	v_cvt_pk_bf16_f32 v31, v32, v33
	v_cvt_pk_bf16_f32 v32, v26, v27
	v_mov_b64_e32 v[26:27], s[58:59]
	v_mad_i64_i32 v[26:27], s[2:3], v52, s57, v[26:27]
	v_cvt_pk_bf16_f32 v33, v28, v29
	v_lshl_add_u64 v[26:27], v[62:63], 1, v[26:27]
	global_store_dwordx4 v[26:27], v[30:33], off offset:256
	s_and_b64 vcc, exec, s[40:41]
	v_add_u32_e32 v44, 0x90, v171
	s_cbranch_vccnz .LBB0_1048
	v_cmp_gt_i32_e32 vcc, s89, v44
	v_and_b32_e32 v26, 0xfdf, v44
	v_and_b32_e32 v27, 64, v248
	v_cndmask_b32_e32 v26, v167, v26, vcc
	v_lshl_or_b32 v30, v26, 7, v84
	v_xor_b32_e32 v26, 32, v248
	v_add_u32_e32 v27, 64, v27
	v_cmp_lt_i32_e32 vcc, v26, v27
	s_nop 1
	v_cndmask_b32_e32 v26, v248, v26, vcc
	v_lshlrev_b32_e32 v45, 2, v26
	ds_bpermute_b32 v46, v45, v22
	ds_bpermute_b32 v47, v45, v23
	s_waitcnt lgkmcnt(0)
	v_pk_mul_f32 v[46:47], v[144:145], v[46:47]
	s_waitcnt vmcnt(1)
	v_mov_b64_e32 v[26:27], v[188:189]
	v_mov_b64_e32 v[28:29], v[190:191]
	v_mov_b64_e32 v[40:41], v[184:185]
	v_mov_b64_e32 v[42:43], v[186:187]
	v_mov_b64_e32 v[36:37], v[180:181]
	v_mov_b64_e32 v[38:39], v[182:183]
	v_mov_b64_e32 v[32:33], v[176:177]
	v_mov_b64_e32 v[34:35], v[178:179]
	v_add_u32_e32 v192, 0xa0, v171
	v_cmp_gt_i32_e32 vcc, s89, v192
	v_and_b32_e32 v192, 0xfef, v192
	v_lshlrev_b32_e32 v193, 2, v165
	v_cndmask_b32_e32 v192, v168, v192, vcc
	v_lshl_or_b32 v192, v192, 7, v193
	global_load_dwordx4 v[188:191], v192, s[0:1] offset:48
	global_load_dwordx4 v[184:187], v192, s[0:1] offset:32
	global_load_dwordx4 v[180:183], v192, s[0:1] offset:16
	global_load_dwordx4 v[176:179], v192, s[0:1]
	v_mov_b32_e32 v31, v34
	v_mov_b32_e32 v34, v33
	v_mov_b32_e32 v30, v32
	v_pk_mul_f32 v[32:33], v[34:35], v[46:47]
	ds_bpermute_b32 v46, v45, v24
	ds_bpermute_b32 v47, v45, v25
	v_mov_b32_e32 v35, v38
	v_mov_b32_e32 v38, v37
	v_mov_b32_e32 v34, v36
	v_pk_fma_f32 v[22:23], v[22:23], v[30:31], v[32:33]
	s_waitcnt lgkmcnt(0)
	v_pk_mul_f32 v[46:47], v[144:145], v[46:47]
	s_nop 0
	v_pk_mul_f32 v[36:37], v[38:39], v[46:47]
	ds_bpermute_b32 v46, v45, v18
	ds_bpermute_b32 v47, v45, v19
	v_mov_b32_e32 v39, v42
	v_mov_b32_e32 v42, v41
	v_mov_b32_e32 v38, v40
	v_pk_fma_f32 v[24:25], v[24:25], v[34:35], v[36:37]
	s_waitcnt lgkmcnt(0)
	v_pk_mul_f32 v[46:47], v[144:145], v[46:47]
	s_nop 0
	v_pk_mul_f32 v[40:41], v[42:43], v[46:47]
	ds_bpermute_b32 v42, v45, v20
	ds_bpermute_b32 v43, v45, v21
	v_mul_f32_e32 v20, v20, v26
	v_pk_fma_f32 v[18:19], v[18:19], v[38:39], v[40:41]
	s_waitcnt lgkmcnt(1)
	v_mul_f32_e32 v26, v144, v42
	s_waitcnt lgkmcnt(0)
	v_mul_f32_e32 v43, v144, v43
	v_mov_b32_e32 v42, v21
	v_pk_mul_f32 v[28:29], v[28:29], v[42:43]
	v_mul_f32_e32 v26, v27, v26
	v_mov_b32_e32 v21, v28
	v_mov_b32_e32 v27, v29
	v_pk_add_f32 v[20:21], v[20:21], v[26:27]
; __device__ __forceinline__ unsigned cvtpk(float lo, float hi) { f32x2_t v = {lo, hi}; bf16x2_t b = __builtin_convertvector(v, bf16x2_t); return __builtin_bit_cast(unsigned, b); }
;     __device__ __forceinline__ void operator()(const f32x4 (&acc)[2][2][4][2], const Unit& u, int wr, int wc, int fr, int fq) const {
;     ...
;                     const int r = EPI_ROW(u, ai, wr, m, fr);
;                     float v[8];
; #pragma unroll
;                     for (int e = 0; e < 4; ++e) { v[e] = acc[ai][bj][m][0][e]; v[4 + e] = acc[ai][bj][m][1][e]; }
;                     if (isrope) {
;                         const int pos = pos_of(r);
;                         const int i0 = (8 * fq) & 15;
;                         const float* rp = rope + ((size_t)pos * 16 + i0) * 2;
;                         const float sg = (fq < 2) ? -1.f : 1.f;
; #pragma unroll
;                         for (int e2 = 0; e2 < 4; ++e2) {
;                             const f32x4 t4 = *(const f32x4*)(rp + 4 * e2);
;                             const float pv0 = __shfl_xor(v[2 * e2], 32), pv1 = __shfl_xor(v[2 * e2 + 1], 32);
;                             v[2 * e2] = v[2 * e2] * t4[0] + sg * pv0 * t4[1];
;                             v[2 * e2 + 1] = v[2 * e2 + 1] * t4[2] + sg * pv1 * t4[3];
;                         }
;                     }
;                     u32x4 w; w.x = cvtpk(v[0], v[1]); w.y = cvtpk(v[2], v[3]); w.z = cvtpk(v[4], v[5]); w.w = cvtpk(v[6], v[7]);
;                     *(u32x4*)(QC + (size_t)r * 576 + c0) = w;
.LBB0_1048:
	v_cvt_pk_bf16_f32 v22, v22, v23
	v_cvt_pk_bf16_f32 v23, v24, v25
	v_cvt_pk_bf16_f32 v24, v18, v19
	v_mov_b64_e32 v[18:19], s[58:59]
	v_mad_i64_i32 v[18:19], s[2:3], v44, s57, v[18:19]
	v_cvt_pk_bf16_f32 v25, v20, v21
	v_lshl_add_u64 v[18:19], v[62:63], 1, v[18:19]
	global_store_dwordx4 v[18:19], v[22:25], off offset:256
	s_and_b64 vcc, exec, s[40:41]
	v_add_u32_e32 v36, 0xa0, v171
	s_cbranch_vccnz .LBB0_1050
	v_cmp_gt_i32_e32 vcc, s89, v36
	v_and_b32_e32 v18, 0xfef, v36
	v_and_b32_e32 v19, 64, v248
	v_cndmask_b32_e32 v18, v168, v18, vcc
	v_lshl_or_b32 v22, v18, 7, v84
	v_xor_b32_e32 v18, 32, v248
	v_add_u32_e32 v19, 64, v19
	v_cmp_lt_i32_e32 vcc, v18, v19
	s_nop 1
	v_cndmask_b32_e32 v18, v248, v18, vcc
	v_lshlrev_b32_e32 v37, 2, v18
	ds_bpermute_b32 v38, v37, v14
	ds_bpermute_b32 v39, v37, v15
	s_waitcnt lgkmcnt(0)
	v_pk_mul_f32 v[38:39], v[144:145], v[38:39]
	s_waitcnt vmcnt(1)
	v_mov_b64_e32 v[18:19], v[188:189]
	v_mov_b64_e32 v[20:21], v[190:191]
	v_mov_b64_e32 v[32:33], v[184:185]
	v_mov_b64_e32 v[34:35], v[186:187]
	v_mov_b64_e32 v[28:29], v[180:181]
	v_mov_b64_e32 v[30:31], v[182:183]
	v_mov_b64_e32 v[24:25], v[176:177]
	v_mov_b64_e32 v[26:27], v[178:179]
	v_add_u32_e32 v192, 0xb0, v171
	v_cmp_gt_i32_e32 vcc, s89, v192
	v_and_b32_e32 v192, 0xfff, v192
	v_lshlrev_b32_e32 v193, 2, v165
	v_cndmask_b32_e32 v192, v169, v192, vcc
	v_lshl_or_b32 v192, v192, 7, v193
	global_load_dwordx4 v[188:191], v192, s[0:1] offset:48
	global_load_dwordx4 v[184:187], v192, s[0:1] offset:32
	global_load_dwordx4 v[180:183], v192, s[0:1] offset:16
	global_load_dwordx4 v[176:179], v192, s[0:1]
	v_mov_b32_e32 v23, v26
	v_mov_b32_e32 v26, v25
	v_mov_b32_e32 v22, v24
	v_pk_mul_f32 v[24:25], v[26:27], v[38:39]
	ds_bpermute_b32 v38, v37, v16
	ds_bpermute_b32 v39, v37, v17
	v_mov_b32_e32 v27, v30
	v_mov_b32_e32 v30, v29
	v_mov_b32_e32 v26, v28
	v_pk_fma_f32 v[14:15], v[14:15], v[22:23], v[24:25]
	s_waitcnt lgkmcnt(0)
	v_pk_mul_f32 v[38:39], v[144:145], v[38:39]
	s_nop 0
	v_pk_mul_f32 v[28:29], v[30:31], v[38:39]
	ds_bpermute_b32 v38, v37, v10
	ds_bpermute_b32 v39, v37, v11
	v_mov_b32_e32 v31, v34
	v_mov_b32_e32 v34, v33
	v_mov_b32_e32 v30, v32
	v_pk_fma_f32 v[16:17], v[16:17], v[26:27], v[28:29]
	s_waitcnt lgkmcnt(0)
	v_pk_mul_f32 v[38:39], v[144:145], v[38:39]
	s_nop 0
	v_pk_mul_f32 v[32:33], v[34:35], v[38:39]
	ds_bpermute_b32 v34, v37, v12
	ds_bpermute_b32 v35, v37, v13
	v_mul_f32_e32 v12, v12, v18
	v_pk_fma_f32 v[10:11], v[10:11], v[30:31], v[32:33]
	s_waitcnt lgkmcnt(1)
	v_mul_f32_e32 v18, v144, v34
	s_waitcnt lgkmcnt(0)
	v_mul_f32_e32 v35, v144, v35
	v_mov_b32_e32 v34, v13
	v_pk_mul_f32 v[20:21], v[20:21], v[34:35]
	v_mul_f32_e32 v18, v19, v18
	v_mov_b32_e32 v13, v20
	v_mov_b32_e32 v19, v21
	v_pk_add_f32 v[12:13], v[12:13], v[18:19]
.LBB0_1050:
	v_cvt_pk_bf16_f32 v14, v14, v15
	v_cvt_pk_bf16_f32 v15, v16, v17
	v_cvt_pk_bf16_f32 v16, v10, v11
	v_mov_b64_e32 v[10:11], s[58:59]
	v_mad_i64_i32 v[10:11], s[2:3], v36, s57, v[10:11]
	v_cvt_pk_bf16_f32 v17, v12, v13
	v_lshl_add_u64 v[10:11], v[62:63], 1, v[10:11]
	global_store_dwordx4 v[10:11], v[14:17], off offset:256
	s_and_b64 vcc, exec, s[40:41]
	v_add_u32_e32 v28, 0xb0, v171
	s_cbranch_vccnz .LBB0_1052
	v_cmp_gt_i32_e32 vcc, s89, v28
	v_and_b32_e32 v10, 0xfff, v28
	v_and_b32_e32 v11, 64, v248
	v_cndmask_b32_e32 v10, v169, v10, vcc
	v_lshl_or_b32 v14, v10, 7, v84
	v_xor_b32_e32 v10, 32, v248
	v_add_u32_e32 v11, 64, v11
	v_cmp_lt_i32_e32 vcc, v10, v11
	s_nop 1
	v_cndmask_b32_e32 v10, v248, v10, vcc
	v_lshlrev_b32_e32 v29, 2, v10
	ds_bpermute_b32 v30, v29, v6
	ds_bpermute_b32 v31, v29, v7
	s_waitcnt lgkmcnt(0)
	v_pk_mul_f32 v[30:31], v[144:145], v[30:31]
	s_waitcnt vmcnt(1)
	v_mov_b64_e32 v[10:11], v[188:189]
	v_mov_b64_e32 v[12:13], v[190:191]
	v_mov_b64_e32 v[24:25], v[184:185]
	v_mov_b64_e32 v[26:27], v[186:187]
	v_mov_b64_e32 v[20:21], v[180:181]
	v_mov_b64_e32 v[22:23], v[182:183]
	v_mov_b64_e32 v[16:17], v[176:177]
	v_mov_b64_e32 v[18:19], v[178:179]
	v_mov_b32_e32 v15, v18
	v_mov_b32_e32 v18, v17
	v_mov_b32_e32 v14, v16
	v_pk_mul_f32 v[16:17], v[18:19], v[30:31]
	ds_bpermute_b32 v30, v29, v8
	ds_bpermute_b32 v31, v29, v9
	v_mov_b32_e32 v19, v22
	v_mov_b32_e32 v22, v21
	v_mov_b32_e32 v18, v20
	v_pk_fma_f32 v[6:7], v[6:7], v[14:15], v[16:17]
	s_waitcnt lgkmcnt(0)
	v_pk_mul_f32 v[30:31], v[144:145], v[30:31]
	s_nop 0
	v_pk_mul_f32 v[20:21], v[22:23], v[30:31]
	ds_bpermute_b32 v30, v29, v0
	ds_bpermute_b32 v31, v29, v1
	v_mov_b32_e32 v23, v26
	v_mov_b32_e32 v26, v25
	v_mov_b32_e32 v22, v24
	v_pk_fma_f32 v[8:9], v[8:9], v[18:19], v[20:21]
	s_waitcnt lgkmcnt(0)
	v_pk_mul_f32 v[30:31], v[144:145], v[30:31]
	s_nop 0
	v_pk_mul_f32 v[24:25], v[26:27], v[30:31]
	ds_bpermute_b32 v26, v29, v2
	ds_bpermute_b32 v27, v29, v3
	v_mul_f32_e32 v2, v2, v10
	v_pk_fma_f32 v[0:1], v[0:1], v[22:23], v[24:25]
	s_waitcnt lgkmcnt(1)
	v_mul_f32_e32 v10, v144, v26
	s_waitcnt lgkmcnt(0)
	v_mul_f32_e32 v27, v144, v27
	v_mov_b32_e32 v26, v3
	v_pk_mul_f32 v[12:13], v[12:13], v[26:27]
	v_mul_f32_e32 v10, v11, v10
	v_mov_b32_e32 v3, v12
	v_mov_b32_e32 v11, v13
	v_pk_add_f32 v[2:3], v[2:3], v[10:11]
